# attention item epilogue de-serialised: gain quads loaded ahead (steps 1-4 with hipcc's early load, 5-7 during steps 4 and 0), stores no longer waited for between steps (8 round trips -> 2)
# speedup vs baseline: 1.0033x; 1.0033x over previous
; __device__ __forceinline__ void attn_item(const Args& A, LAS unsigned char* lds, int b, int h, int qb, float lam) {
;     ...
;     float inv[2];
; #pragma unroll
;     for (int p = 0; p < 2; ++p) { const float lt = xrow_sum(lrun[p]); inv[p] = 1.f / lt; }
;     float ss = 0.f;
; #pragma unroll
;     for (int vt = 0; vt < 8; ++vt)
; #pragma unroll
;         for (int r = 0; r < 4; ++r) { const float ov = o[0][vt][r] * inv[0] - lam * (o[1][vt][r] * inv[1]); o[0][vt][r] = ov; ss += ov * ov; }
;     ss = xrow_sum(ss);
;     const float rstd = rsqrtf(ss * (1.f / 128.f) + 1e-6f) * 0.8f;
;     bf16_t* op = ACT + (rowbase + qabs) * 1024 + 512 + h * 128 + 4 * g;
; #pragma unroll
;     for (int vt = 0; vt < 8; ++vt) { const f32x4 gn = *(const f32x4*)(A.dnorm_g + 16 * vt + 4 * g);
.LBB0_313:
	s_or_b64 exec, exec, s[72:73]
	v_mov_b32_e32 v64, v133
	s_nop 1
	v_permlane16_swap_b32_e32 v133, v64
	v_add_f32_e32 v64, v133, v64
	v_mov_b32_e32 v65, v64
	s_nop 1
	v_permlane32_swap_b32_e32 v64, v65
	v_add_f32_e32 v64, v64, v65
	v_div_scale_f32 v65, s[0:1], v64, v64, 1.0
	v_rcp_f32_e32 v66, v65
	v_ashrrev_i32_e32 v133, 31, v132
	s_barrier
	v_fma_f32 v67, -v65, v66, 1.0
	v_fmac_f32_e32 v66, v67, v66
	v_div_scale_f32 v67, vcc, 1.0, v64, 1.0
	v_mul_f32_e32 v68, v67, v66
	v_fma_f32 v69, -v65, v68, v67
	v_fmac_f32_e32 v68, v69, v66
	v_fma_f32 v65, -v65, v68, v67
	v_mov_b32_e32 v67, v144
	s_nop 1
	v_permlane16_swap_b32_e32 v144, v67
	v_add_f32_e32 v67, v144, v67
	v_mov_b32_e32 v69, v67
	s_nop 1
	v_permlane32_swap_b32_e32 v67, v69
	v_add_f32_e32 v67, v67, v69
	v_div_scale_f32 v69, s[0:1], v67, v67, 1.0
	v_rcp_f32_e32 v70, v69
	v_div_fmas_f32 v65, v65, v66, v68
	v_div_fixup_f32 v68, v65, v64, 1.0
	v_fma_f32 v64, -v69, v70, 1.0
	v_fmac_f32_e32 v70, v64, v70
	v_div_scale_f32 v64, vcc, 1.0, v67, 1.0
	v_mul_f32_e32 v65, v64, v70
	v_fma_f32 v66, -v69, v65, v64
	v_fmac_f32_e32 v65, v66, v70
	v_fma_f32 v64, -v69, v65, v64
	v_div_fmas_f32 v64, v64, v70, v65
	v_div_fixup_f32 v70, v64, v67, 1.0
	v_lshl_add_u64 v[64:65], v[132:133], 0, s[62:63]
	v_lshlrev_b64 v[64:65], 11, v[64:65]
	v_lshlrev_b32_e32 v69, 2, v143
	v_lshl_add_u64 v[72:73], s[50:51], 0, v[64:65]
	global_load_dwordx4 v[64:67], v69, s[80:81]
	global_load_dwordx4 v[240:243], v69, s[80:81] offset:64
	global_load_dwordx4 v[244:247], v69, s[80:81] offset:128
	global_load_dwordx4 v[248:251], v69, s[80:81] offset:192
	global_load_dwordx4 v[252:255], v69, s[80:81] offset:256
	v_pk_mul_f32 v[56:57], v[56:57], v[70:71] op_sel_hi:[1,0]
	v_pk_mul_f32 v[58:59], v[58:59], v[70:71] op_sel_hi:[1,0]
	v_pk_mul_f32 v[56:57], v[130:131], v[56:57]
	v_pk_mul_f32 v[58:59], v[130:131], v[58:59]
	v_pk_fma_f32 v[56:57], v[60:61], v[68:69], v[56:57] op_sel_hi:[1,0,1] neg_lo:[0,0,1] neg_hi:[0,0,1]
	v_pk_fma_f32 v[58:59], v[62:63], v[68:69], v[58:59] op_sel_hi:[1,0,1] neg_lo:[0,0,1] neg_hi:[0,0,1]
	v_mul_f32_e32 v60, v57, v57
	v_pk_fma_f32 v[60:61], v[56:57], v[56:57], v[60:61] op_sel_hi:[1,1,0]
	v_pk_mul_f32 v[48:49], v[48:49], v[70:71] op_sel_hi:[1,0]
	v_pk_fma_f32 v[60:61], v[58:59], v[58:59], v[60:61]
	v_mul_f32_e32 v62, v59, v59
	v_pk_mul_f32 v[50:51], v[50:51], v[70:71] op_sel_hi:[1,0]
	v_pk_mul_f32 v[48:49], v[130:131], v[48:49]
	v_pk_add_f32 v[60:61], v[62:63], v[60:61] op_sel_hi:[0,1]
	v_pk_mul_f32 v[50:51], v[130:131], v[50:51]
	v_pk_fma_f32 v[48:49], v[52:53], v[68:69], v[48:49] op_sel_hi:[1,0,1] neg_lo:[0,0,1] neg_hi:[0,0,1]
	v_pk_fma_f32 v[50:51], v[54:55], v[68:69], v[50:51] op_sel_hi:[1,0,1] neg_lo:[0,0,1] neg_hi:[0,0,1]
	v_pk_fma_f32 v[52:53], v[48:49], v[48:49], v[60:61]
	v_mul_f32_e32 v54, v49, v49
	v_pk_add_f32 v[52:53], v[54:55], v[52:53] op_sel_hi:[0,1]
	v_pk_mul_f32 v[40:41], v[40:41], v[70:71] op_sel_hi:[1,0]
	v_pk_fma_f32 v[52:53], v[50:51], v[50:51], v[52:53]
	v_mul_f32_e32 v54, v51, v51
	v_pk_mul_f32 v[42:43], v[42:43], v[70:71] op_sel_hi:[1,0]
	v_pk_mul_f32 v[40:41], v[130:131], v[40:41]
	v_pk_add_f32 v[52:53], v[54:55], v[52:53] op_sel_hi:[0,1]
	v_pk_mul_f32 v[42:43], v[130:131], v[42:43]
	v_pk_fma_f32 v[40:41], v[44:45], v[68:69], v[40:41] op_sel_hi:[1,0,1] neg_lo:[0,0,1] neg_hi:[0,0,1]
	v_pk_fma_f32 v[42:43], v[46:47], v[68:69], v[42:43] op_sel_hi:[1,0,1] neg_lo:[0,0,1] neg_hi:[0,0,1]
	v_pk_fma_f32 v[44:45], v[40:41], v[40:41], v[52:53]
	v_mul_f32_e32 v46, v41, v41
	v_pk_add_f32 v[44:45], v[46:47], v[44:45] op_sel_hi:[0,1]
	v_pk_mul_f32 v[32:33], v[32:33], v[70:71] op_sel_hi:[1,0]
	v_pk_fma_f32 v[44:45], v[42:43], v[42:43], v[44:45]
	v_mul_f32_e32 v46, v43, v43
	v_pk_mul_f32 v[34:35], v[34:35], v[70:71] op_sel_hi:[1,0]
	v_pk_mul_f32 v[32:33], v[130:131], v[32:33]
	v_pk_add_f32 v[44:45], v[46:47], v[44:45] op_sel_hi:[0,1]
	v_pk_mul_f32 v[34:35], v[130:131], v[34:35]
	v_pk_fma_f32 v[32:33], v[36:37], v[68:69], v[32:33] op_sel_hi:[1,0,1] neg_lo:[0,0,1] neg_hi:[0,0,1]
	v_pk_fma_f32 v[34:35], v[38:39], v[68:69], v[34:35] op_sel_hi:[1,0,1] neg_lo:[0,0,1] neg_hi:[0,0,1]
	v_pk_fma_f32 v[36:37], v[32:33], v[32:33], v[44:45]
	v_mul_f32_e32 v38, v33, v33
	v_pk_add_f32 v[36:37], v[38:39], v[36:37] op_sel_hi:[0,1]
	v_pk_mul_f32 v[24:25], v[24:25], v[70:71] op_sel_hi:[1,0]
	v_pk_fma_f32 v[36:37], v[34:35], v[34:35], v[36:37]
	v_mul_f32_e32 v38, v35, v35
	v_pk_mul_f32 v[26:27], v[26:27], v[70:71] op_sel_hi:[1,0]
	v_pk_mul_f32 v[24:25], v[130:131], v[24:25]
	v_pk_add_f32 v[36:37], v[38:39], v[36:37] op_sel_hi:[0,1]
	v_pk_mul_f32 v[26:27], v[130:131], v[26:27]
	v_pk_fma_f32 v[24:25], v[28:29], v[68:69], v[24:25] op_sel_hi:[1,0,1] neg_lo:[0,0,1] neg_hi:[0,0,1]
	v_pk_fma_f32 v[26:27], v[30:31], v[68:69], v[26:27] op_sel_hi:[1,0,1] neg_lo:[0,0,1] neg_hi:[0,0,1]
	v_pk_fma_f32 v[28:29], v[24:25], v[24:25], v[36:37]
	v_mul_f32_e32 v30, v25, v25
	v_pk_add_f32 v[28:29], v[30:31], v[28:29] op_sel_hi:[0,1]
	v_pk_mul_f32 v[12:13], v[12:13], v[70:71] op_sel_hi:[1,0]
	v_pk_fma_f32 v[28:29], v[26:27], v[26:27], v[28:29]
	v_mul_f32_e32 v30, v27, v27
	v_pk_mul_f32 v[14:15], v[14:15], v[70:71] op_sel_hi:[1,0]
	v_pk_mul_f32 v[12:13], v[130:131], v[12:13]
	v_pk_add_f32 v[28:29], v[30:31], v[28:29] op_sel_hi:[0,1]
	v_pk_mul_f32 v[14:15], v[130:131], v[14:15]
	v_pk_fma_f32 v[12:13], v[20:21], v[68:69], v[12:13] op_sel_hi:[1,0,1] neg_lo:[0,0,1] neg_hi:[0,0,1]
; __device__ __forceinline__ unsigned pk2(float lo, float hi) { const f32x2 v = {lo, hi}; const bf16x2_t b = __builtin_convertvector(v, bf16x2_t); return __builtin_bit_cast(unsigned, b); }
; __device__ __forceinline__ void attn_item(const Args& A, LAS unsigned char* lds, int b, int h, int qb, float lam) {
;     ...
;         for (int r = 0; r < 4; ++r) { const float ov = o[0][vt][r] * inv[0] - lam * (o[1][vt][r] * inv[1]); o[0][vt][r] = ov; ss += ov * ov; }
;     ss = xrow_sum(ss);
;     const float rstd = rsqrtf(ss * (1.f / 128.f) + 1e-6f) * 0.8f;
;     bf16_t* op = ACT + (rowbase + qabs) * 1024 + 512 + h * 128 + 4 * g;
; #pragma unroll
;     for (int vt = 0; vt < 8; ++vt) { const f32x4 gn = *(const f32x4*)(A.dnorm_g + 16 * vt + 4 * g);
;         u32x2 wv; wv.x = pk2(o[0][vt][0] * rstd * gn[0], o[0][vt][1] * rstd * gn[1]); wv.y = pk2(o[0][vt][2] * rstd * gn[2], o[0][vt][3] * rstd * gn[3]);
;         *(u32x2*)(op + 16 * vt) = wv; }
	v_pk_fma_f32 v[14:15], v[22:23], v[68:69], v[14:15] op_sel_hi:[1,0,1] neg_lo:[0,0,1] neg_hi:[0,0,1]
	v_pk_fma_f32 v[20:21], v[12:13], v[12:13], v[28:29]
	v_mul_f32_e32 v22, v13, v13
	v_pk_add_f32 v[20:21], v[22:23], v[20:21] op_sel_hi:[0,1]
	v_pk_mul_f32 v[16:17], v[16:17], v[70:71] op_sel_hi:[1,0]
	v_pk_fma_f32 v[20:21], v[14:15], v[14:15], v[20:21]
	v_mul_f32_e32 v22, v15, v15
	v_pk_mul_f32 v[18:19], v[18:19], v[70:71] op_sel_hi:[1,0]
	v_pk_mul_f32 v[16:17], v[130:131], v[16:17]
	v_pk_add_f32 v[20:21], v[22:23], v[20:21] op_sel_hi:[0,1]
	v_pk_mul_f32 v[18:19], v[130:131], v[18:19]
	v_pk_fma_f32 v[8:9], v[8:9], v[68:69], v[16:17] op_sel_hi:[1,0,1] neg_lo:[0,0,1] neg_hi:[0,0,1]
	v_pk_mul_f32 v[6:7], v[6:7], v[70:71] op_sel_hi:[1,0]
	v_pk_fma_f32 v[10:11], v[10:11], v[68:69], v[18:19] op_sel_hi:[1,0,1] neg_lo:[0,0,1] neg_hi:[0,0,1]
	v_pk_fma_f32 v[16:17], v[8:9], v[8:9], v[20:21]
	v_mul_f32_e32 v18, v9, v9
	v_pk_mul_f32 v[6:7], v[130:131], v[6:7]
	v_pk_add_f32 v[16:17], v[18:19], v[16:17] op_sel_hi:[0,1]
	v_pk_fma_f32 v[6:7], v[2:3], v[68:69], v[6:7] op_sel_hi:[1,0,1] neg_lo:[0,0,1] neg_hi:[0,0,1]
	v_pk_mul_f32 v[2:3], v[4:5], v[70:71] op_sel_hi:[1,0]
	v_pk_fma_f32 v[16:17], v[10:11], v[10:11], v[16:17]
	v_mul_f32_e32 v18, v11, v11
	v_pk_mul_f32 v[2:3], v[130:131], v[2:3]
	v_pk_add_f32 v[16:17], v[18:19], v[16:17] op_sel_hi:[0,1]
	v_pk_fma_f32 v[4:5], v[0:1], v[68:69], v[2:3] op_sel_hi:[1,0,1] neg_lo:[0,0,1] neg_hi:[0,0,1]
	s_lshl_b32 s62, s91, 1
	v_pk_fma_f32 v[0:1], v[4:5], v[4:5], v[16:17]
	v_mul_f32_e32 v2, v5, v5
	v_pk_add_f32 v[0:1], v[2:3], v[0:1] op_sel_hi:[0,1]
	v_pk_fma_f32 v[0:1], v[6:7], v[6:7], v[0:1]
	v_mul_f32_e32 v2, v7, v7
	v_pk_add_f32 v[0:1], v[2:3], v[0:1] op_sel_hi:[0,1]
	v_mov_b32_e32 v1, v0
	s_nop 1
	v_permlane16_swap_b32_e32 v0, v1
	v_add_f32_e32 v0, v0, v1
	v_mov_b32_e32 v1, v0
	s_nop 1
	v_permlane32_swap_b32_e32 v0, v1
	v_add_f32_e32 v0, v0, v1
	v_fmamk_f32 v0, v0, 0x3c000000, v140
	v_mul_f32_e32 v1, 0x4b800000, v0
	v_cmp_gt_f32_e32 vcc, s89, v0
	v_lshlrev_b32_e32 v128, 1, v143
	s_mov_b64 s[0:1], 0
	v_cndmask_b32_e32 v0, v0, v1, vcc
	v_rsq_f32_e32 v2, v0
	v_lshl_add_u64 v[0:1], v[72:73], 0, s[62:63]
	v_lshl_add_u64 v[16:17], v[0:1], 0, v[128:129]
	v_mul_f32_e32 v0, 0x45800000, v2
	v_cndmask_b32_e32 v0, v2, v0, vcc
	v_mul_f32_e32 v18, 0x3f4ccccd, v0
	v_pk_mul_f32 v[0:1], v[56:57], v[18:19] op_sel_hi:[1,0]
	v_pk_mul_f32 v[2:3], v[58:59], v[18:19] op_sel_hi:[1,0]
	s_waitcnt vmcnt(0)
	v_add_co_u32_e32 v238, vcc, s90, v16
	s_nop 1
	v_addc_co_u32_e32 v239, vcc, 0, v17, vcc
	v_lshl_add_u64 v[16:17], v[16:17], 0, s[68:69]
	v_pk_mul_f32 v[20:21], v[48:49], v[18:19] op_sel_hi:[1,0]
	v_pk_mul_f32 v[22:23], v[50:51], v[18:19] op_sel_hi:[1,0]
	v_pk_mul_f32 v[0:1], v[240:241], v[20:21]
	v_pk_mul_f32 v[2:3], v[242:243], v[22:23]
	v_cvt_pk_bf16_f32 v0, v0, v1
	v_cvt_pk_bf16_f32 v1, v2, v3
	global_store_dwordx2 v[16:17], v[0:1], off offset:32
	s_nop 1
	v_pk_mul_f32 v[20:21], v[40:41], v[18:19] op_sel_hi:[1,0]
	v_pk_mul_f32 v[22:23], v[42:43], v[18:19] op_sel_hi:[1,0]
	v_pk_mul_f32 v[0:1], v[244:245], v[20:21]
	v_pk_mul_f32 v[2:3], v[246:247], v[22:23]
	v_cvt_pk_bf16_f32 v0, v0, v1
	v_cvt_pk_bf16_f32 v1, v2, v3
	global_store_dwordx2 v[16:17], v[0:1], off offset:64
	s_nop 1
	v_pk_mul_f32 v[20:21], v[32:33], v[18:19] op_sel_hi:[1,0]
	v_pk_mul_f32 v[22:23], v[34:35], v[18:19] op_sel_hi:[1,0]
	v_pk_mul_f32 v[0:1], v[248:249], v[20:21]
	v_pk_mul_f32 v[2:3], v[250:251], v[22:23]
	v_cvt_pk_bf16_f32 v0, v0, v1
	v_cvt_pk_bf16_f32 v1, v2, v3
	global_store_dwordx2 v[16:17], v[0:1], off offset:96
	s_nop 1
	global_load_dwordx4 v[240:243], v69, s[80:81] offset:320
	global_load_dwordx4 v[244:247], v69, s[80:81] offset:384
	global_load_dwordx4 v[248:251], v69, s[80:81] offset:448
	v_pk_mul_f32 v[20:21], v[24:25], v[18:19] op_sel_hi:[1,0]
	v_pk_mul_f32 v[22:23], v[26:27], v[18:19] op_sel_hi:[1,0]
	v_pk_mul_f32 v[0:1], v[252:253], v[20:21]
	v_pk_mul_f32 v[2:3], v[254:255], v[22:23]
	v_cvt_pk_bf16_f32 v0, v0, v1
	v_cvt_pk_bf16_f32 v1, v2, v3
	global_store_dwordx2 v[16:17], v[0:1], off offset:128
	s_nop 1
	v_pk_mul_f32 v[20:21], v[56:57], v[18:19] op_sel_hi:[1,0]
	v_pk_mul_f32 v[22:23], v[58:59], v[18:19] op_sel_hi:[1,0]
	v_pk_mul_f32 v[0:1], v[64:65], v[20:21]
	v_pk_mul_f32 v[2:3], v[66:67], v[22:23]
	v_cvt_pk_bf16_f32 v0, v0, v1
	v_cvt_pk_bf16_f32 v1, v2, v3
	global_store_dwordx2 v[238:239], v[0:1], off offset:1024
	s_nop 1
	v_pk_mul_f32 v[12:13], v[12:13], v[18:19] op_sel_hi:[1,0]
	v_pk_mul_f32 v[14:15], v[14:15], v[18:19] op_sel_hi:[1,0]
	v_pk_mul_f32 v[8:9], v[8:9], v[18:19] op_sel_hi:[1,0]
	v_pk_mul_f32 v[10:11], v[10:11], v[18:19] op_sel_hi:[1,0]
	v_pk_mul_f32 v[4:5], v[4:5], v[18:19] op_sel_hi:[1,0]
	v_pk_mul_f32 v[6:7], v[6:7], v[18:19] op_sel_hi:[1,0]
	s_waitcnt vmcnt(0)
	v_pk_mul_f32 v[0:1], v[12:13], v[240:241]
	v_pk_mul_f32 v[2:3], v[14:15], v[242:243]
	v_cvt_pk_bf16_f32 v0, v0, v1
	v_cvt_pk_bf16_f32 v1, v2, v3
	global_store_dwordx2 v[16:17], v[0:1], off offset:160
	s_nop 1
	v_pk_mul_f32 v[0:1], v[8:9], v[244:245]
	v_pk_mul_f32 v[2:3], v[10:11], v[246:247]
	v_cvt_pk_bf16_f32 v0, v0, v1
	v_cvt_pk_bf16_f32 v1, v2, v3
	global_store_dwordx2 v[16:17], v[0:1], off offset:192
	s_nop 1
	v_pk_mul_f32 v[0:1], v[4:5], v[248:249]
	v_pk_mul_f32 v[2:3], v[6:7], v[250:251]
	v_cvt_pk_bf16_f32 v0, v0, v1
	v_cvt_pk_bf16_f32 v1, v2, v3
	global_store_dwordx2 v[16:17], v[0:1], off offset:224
	s_nop 1
